# lever 2 on the GEMM phase prologue: second group of ring stages (6 LDS-DMA) issued before the first wait+barrier (wait becomes vmcnt(8)); once per GEMM phase
# baseline (speedup 1.0000x reference)
; #define PG8_STAGE(bufoff, gbase, voff) do { _Pragma("unroll") for (int _i = 0; _i < 2; ++_i) \
;         __builtin_amdgcn_global_load_lds((const unsigned*)((const char*)(gbase) + (voff)[_i]), (LAS unsigned*)(lds + (bufoff) + ldsw + _i * 8192), 16, 0, 0); } while (0)
; #define PG8_WAIT_V(n) asm volatile("s_waitcnt vmcnt(" #n ")" ::: "memory")
; #define PG8_BAR __builtin_amdgcn_s_barrier()
; template <class Epi, class Sched, bool ALIGN_EPI = true>
; __device__ __forceinline__ void gemm_phase(LAS unsigned char* lds, const int wave_s, const int K, const Sched& S, const Epi& E) {
;     ...
;     PG8_STAGE(PG8_SB(0, 0), cB, voffB); PG8_STAGE(PG8_SB(0, 1), cB + hstep, voffB); PG8_STAGE(PG8_SA(0, 0), cA, voffA); PG8_STAGE(PG8_SA(0, 1), cA + hstep, voffA);
;     if (wr == 1) PG8_BAR;
;     PG8_WAIT_V(2); PG8_BAR;
;     PG8_STAGE(PG8_SB(1, 0), cB + kstep, voffB); PG8_STAGE(PG8_SA(1, 0), cA + kstep, voffA); PG8_STAGE(PG8_SB(1, 1), cB + hstep + kstep, voffB);
;     PG8_WAIT_V(6); PG8_BAR;
.LBB0_55:
	v_readlane_b32 s46, v254, 60
	s_lshl_b32 s36, s46, 1
	v_readlane_b32 s47, v254, 61
	s_or_b32 s46, s36, 1
	s_ashr_i32 s47, s46, 31
	s_lshl_b64 s[48:49], s[46:47], 19
	s_add_u32 s48, s10, s48
	s_addc_u32 s49, s11, s49
	s_add_u32 s36, s48, 0x12f00000
	s_addc_u32 s39, s49, 0
	s_lshl_b32 s46, s46, 13
	s_ashr_i32 s47, s46, 31
	s_lshl_b64 s[46:47], s[46:47], 2
	s_add_u32 s43, s10, s46
	s_addc_u32 s46, s11, s47
	s_add_u32 s56, s43, 0x4000
	s_addc_u32 s57, s46, 0
	s_ashr_i32 s43, s42, 31
	s_lshl_b64 s[42:43], s[42:43], 2
	s_waitcnt lgkmcnt(0)
	s_add_u32 s52, s44, s42
	s_addc_u32 s53, s45, s43
	v_lshl_add_u64 v[2:3], v[2:3], 0, s[22:23]
	s_add_i32 m0, s20, 0x18000
	s_nop 1
	global_load_lds_dwordx4 v[2:3], off
	v_lshl_add_u64 v[2:3], v[4:5], 0, s[22:23]
	s_add_i32 m0, s20, 0x1a000
	s_add_i32 s72, s20, 0x8000
	s_add_i32 s73, s20, 0xa000
	global_load_lds_dwordx4 v[2:3], off
	v_lshl_add_u64 v[2:3], v[6:7], 0, s[22:23]
	s_mov_b32 m0, s72
	s_add_u32 s42, s50, 0x100080
	global_load_lds_dwordx4 v[2:3], off
	v_lshl_add_u64 v[2:3], v[8:9], 0, s[22:23]
	s_mov_b32 m0, s73
	s_addc_u32 s43, s51, 0
	global_load_lds_dwordx4 v[2:3], off
	v_lshl_add_u64 v[2:3], s[42:43], 0, v[0:1]
	s_add_i32 m0, s20, 0x1c000
	v_readlane_b32 s44, v253, 14
	global_load_lds_dwordx4 v[2:3], off
	v_lshl_add_u64 v[2:3], s[42:43], 0, v[134:135]
	s_add_i32 m0, s20, 0x1e000
	v_readlane_b32 s42, v253, 6
	global_load_lds_dwordx4 v[2:3], off
	s_waitcnt vmcnt(8)
	s_barrier
	v_and_b32_e32 v3, 15, v15
	v_bfe_u32 v2, v15, 4, 2
	v_or_b32_e32 v170, s42, v3
	v_lshlrev_b32_e32 v4, 6, v170
	v_lshlrev_b32_e32 v5, 4, v2
	s_movk_i32 s42, 0x3c0
	v_lshlrev_b32_e32 v6, 2, v170
	v_and_or_b32 v4, v4, s42, v5
	v_and_b32_e32 v7, 32, v6
	v_readlane_b32 s42, v253, 7
	v_lshl_or_b32 v5, v3, 6, v5
	s_add_i32 s54, 0, 0x21000
	v_bitop3_b32 v4, v4, s42, v7 bitop3:0xde
	v_lshlrev_b32_e32 v7, 2, v15
	v_and_b32_e32 v7, 32, v7
	v_readlane_b32 s42, v253, 9
	s_ashr_i32 s87, s29, 31
	s_waitcnt vmcnt(6)
	v_lshlrev_b32_e32 v3, 4, v3
	v_bitop3_b32 v171, v5, s42, v7 bitop3:0xde
	v_and_b32_e32 v5, 63, v15
	v_lshlrev_b32_e32 v7, 2, v5
	v_xor_b32_e32 v172, 64, v7
	v_or_b32_e32 v7, s44, v5
	s_movk_i32 s44, 0x100
	v_cmp_gt_i32_e64 s[44:45], s44, v7
	v_cmp_eq_u32_e64 s[46:47], 0, v5
	s_and_b64 s[60:61], s[46:47], s[44:45]
	v_lshl_add_u32 v180, v7, 4, s54
	s_add_i32 s54, 0, 0x22000
	s_cmp_lg_u64 s[14:15], 0
	s_cselect_b64 s[62:63], -1, 0
	s_add_u32 s92, s48, 0x12f40000
	v_readlane_b32 s48, v253, 8
	v_cmp_eq_u32_e64 s[42:43], 0, v2
	v_and_b32_e32 v5, 1, v10
	v_lshl_or_b32 v190, v2, 3, s48
	v_lshlrev_b32_e32 v2, 16, v10
	v_and_b32_e32 v2, 0xfffe0000, v2
	v_lshl_add_u32 v2, v11, 13, v2
	v_lshl_or_b32 v2, v5, 6, v2
	v_lshl_add_u32 v138, v12, 1, v2
	v_lshlrev_b32_e32 v2, 16, v13
	v_and_b32_e32 v2, 0xfffe0000, v2
	v_lshl_add_u32 v2, v14, 13, v2
	v_and_b32_e32 v5, 1, v13
	v_lshlrev_b32_e32 v136, 2, v7
	v_or_b32_e32 v173, 16, v170
	v_or_b32_e32 v174, 32, v170
	v_or_b32_e32 v175, 48, v170
	v_add_u32_e32 v176, 0x80, v170
	v_add_u32_e32 v177, 0x90, v170
	v_add_u32_e32 v178, 0xa0, v170
	v_add_u32_e32 v179, 0xb0, v170
	v_lshl_or_b32 v2, v5, 6, v2
	v_readlane_b32 s48, v253, 17
	s_mov_b32 s86, 0
	v_ashrrev_i32_e32 v137, 31, v136
	v_add_u32_e32 v181, s54, v136
	v_add_u32_e32 v182, s54, v6
	v_lshl_add_u32 v183, v173, 2, s54
	v_lshl_add_u32 v184, v174, 2, s54
	v_lshl_add_u32 v185, v175, 2, s54
	v_lshl_add_u32 v186, v176, 2, s54
	v_lshl_add_u32 v187, v177, 2, s54
	v_lshl_add_u32 v188, v178, 2, s54
	v_lshl_add_u32 v189, v179, 2, s54
	s_addc_u32 s94, s49, 0
	v_mov_b32_e32 v139, v1
	v_lshl_add_u32 v140, v16, 1, v2
	v_mov_b32_e32 v141, v1
	v_add_u32_e32 v191, 0, v4
	v_add_u32_e32 v201, s48, v3
	s_barrier
	s_branch .LBB0_58

; #define PG8_STAGE(bufoff, gbase, voff) do { _Pragma("unroll") for (int _i = 0; _i < 2; ++_i) \
;         __builtin_amdgcn_global_load_lds((const unsigned*)((const char*)(gbase) + (voff)[_i]), (LAS unsigned*)(lds + (bufoff) + ldsw + _i * 8192), 16, 0, 0); } while (0)
; #define PG8_WAIT_V(n) asm volatile("s_waitcnt vmcnt(" #n ")" ::: "memory")
; #define PG8_BAR __builtin_amdgcn_s_barrier()
; template <class Epi, class Sched, bool ALIGN_EPI = true>
; __device__ __forceinline__ void gemm_phase(LAS unsigned char* lds, const int wave_s, const int K, const Sched& S, const Epi& E) {
;     ...
;     PG8_STAGE(PG8_SB(0, 0), cB, voffB); PG8_STAGE(PG8_SB(0, 1), cB + hstep, voffB); PG8_STAGE(PG8_SA(0, 0), cA, voffA); PG8_STAGE(PG8_SA(0, 1), cA + hstep, voffA);
;     if (wr == 1) PG8_BAR;
;     PG8_WAIT_V(2); PG8_BAR;
;     PG8_STAGE(PG8_SB(1, 0), cB + kstep, voffB); PG8_STAGE(PG8_SA(1, 0), cA + kstep, voffA); PG8_STAGE(PG8_SB(1, 1), cB + hstep + kstep, voffB);
;     PG8_WAIT_V(6); PG8_BAR;
.LBB0_150:
	v_and_b32_e32 v17, 15, v16
	v_readlane_b32 s14, v253, 6
	v_lshrrev_b32_e32 v18, 1, v16
	v_and_b32_e32 v18, 24, v18
	v_or_b32_e32 v142, s14, v17
	s_add_u32 s12, s10, 0xad00000
	v_lshlrev_b32_e32 v19, 6, v142
	v_lshlrev_b32_e32 v20, 1, v18
	s_movk_i32 s14, 0x3c0
	v_lshlrev_b32_e32 v21, 2, v142
	s_addc_u32 s13, s11, 0
	v_and_or_b32 v19, v19, s14, v20
	v_and_b32_e32 v21, 32, v21
	v_readlane_b32 s14, v253, 7
	v_lshlrev_b32_e32 v16, 2, v16
	v_lshl_add_u64 v[2:3], v[2:3], 0, s[22:23]
	s_add_i32 m0, s18, 0x18000
	v_bitop3_b32 v19, v19, s14, v21 bitop3:0xde
	v_lshl_or_b32 v17, v17, 6, v20
	v_and_b32_e32 v16, 32, v16
	v_readlane_b32 s14, v253, 19
	s_nop 1
	global_load_lds_dwordx4 v[2:3], off
	v_lshl_add_u64 v[2:3], v[4:5], 0, s[22:23]
	s_add_i32 m0, s18, 0x1a000
	s_add_i32 s28, s18, 0x8000
	s_add_i32 s30, s18, 0xa000
	v_bitop3_b32 v143, v17, s14, v16 bitop3:0xde
	global_load_lds_dwordx4 v[2:3], off
	v_lshl_add_u64 v[2:3], v[6:7], 0, s[22:23]
	s_mov_b32 m0, s28
	s_add_u32 s14, s50, 0x40080
	global_load_lds_dwordx4 v[2:3], off
	v_lshl_add_u64 v[2:3], v[8:9], 0, s[22:23]
	s_mov_b32 m0, s30
	s_addc_u32 s15, s51, 0
	global_load_lds_dwordx4 v[2:3], off
	v_lshl_add_u64 v[2:3], s[14:15], 0, v[0:1]
	s_add_i32 m0, s18, 0x1c000
	s_ashr_i32 s36, s29, 31
	global_load_lds_dwordx4 v[2:3], off
	v_lshl_add_u64 v[2:3], s[14:15], 0, v[130:131]
	s_add_i32 m0, s18, 0x1e000
	v_readlane_b32 s14, v253, 18
	global_load_lds_dwordx4 v[2:3], off
	s_waitcnt vmcnt(8)
	s_barrier
	v_lshlrev_b32_e32 v2, 14, v13
	v_and_b32_e32 v2, 0xffff8000, v2
	v_lshl_add_u32 v2, v14, 11, v2
	v_and_b32_e32 v3, 1, v13
	v_lshl_or_b32 v2, v3, 6, v2
	v_lshl_add_u32 v136, v15, 1, v2
	v_lshlrev_b32_e32 v2, 14, v10
	v_or_b32_e32 v144, s14, v18
	v_and_b32_e32 v2, 0xffff8000, v2
	v_readlane_b32 s14, v254, 44
	s_waitcnt vmcnt(6)
	v_lshl_add_u32 v2, v11, 11, v2
	v_and_b32_e32 v3, 1, v10
	v_readlane_b32 s15, v254, 45
	v_lshl_or_b32 v2, v3, 6, v2
	s_mov_b32 s54, s14
	v_readlane_b32 s14, v254, 40
	v_mov_b32_e32 v137, v1
	v_lshl_add_u32 v138, v12, 1, v2
	v_mov_b32_e32 v139, v1
	s_mov_b32 s39, 0
	v_add_u32_e32 v145, 0, v19
	s_mov_b32 s55, s14
	s_barrier
	v_readlane_b32 s15, v254, 41
	s_branch .LBB0_153

; #define PG8_STAGE(bufoff, gbase, voff) do { _Pragma("unroll") for (int _i = 0; _i < 2; ++_i) \
;         __builtin_amdgcn_global_load_lds((const unsigned*)((const char*)(gbase) + (voff)[_i]), (LAS unsigned*)(lds + (bufoff) + ldsw + _i * 8192), 16, 0, 0); } while (0)
; #define PG8_WAIT_V(n) asm volatile("s_waitcnt vmcnt(" #n ")" ::: "memory")
; #define PG8_BAR __builtin_amdgcn_s_barrier()
; template <class Epi, class Sched, bool ALIGN_EPI = true>
; __device__ __forceinline__ void gemm_phase(LAS unsigned char* lds, const int wave_s, const int K, const Sched& S, const Epi& E) {
;     ...
;     PG8_STAGE(PG8_SB(0, 0), cB, voffB); PG8_STAGE(PG8_SB(0, 1), cB + hstep, voffB); PG8_STAGE(PG8_SA(0, 0), cA, voffA); PG8_STAGE(PG8_SA(0, 1), cA + hstep, voffA);
;     if (wr == 1) PG8_BAR;
;     PG8_WAIT_V(2); PG8_BAR;
;     PG8_STAGE(PG8_SB(1, 0), cB + kstep, voffB); PG8_STAGE(PG8_SA(1, 0), cA + kstep, voffA); PG8_STAGE(PG8_SB(1, 1), cB + hstep + kstep, voffB);
;     PG8_WAIT_V(6); PG8_BAR;
.LBB0_187:
	v_readlane_b32 s44, v254, 60
	v_readlane_b32 s45, v254, 61
	s_mov_b32 s20, s44
	s_lshl_b32 s44, s44, 10
	s_ashr_i32 s45, s44, 31
	s_lshl_b64 s[44:45], s[44:45], 2
	s_waitcnt lgkmcnt(0)
	s_add_u32 s52, s42, s44
	s_addc_u32 s53, s43, s45
	s_add_u32 s62, s48, s44
	s_addc_u32 s63, s49, s45
	s_lshl_b32 s42, s20, 1
	s_ashr_i32 s43, s42, 31
	s_lshl_b64 s[42:43], s[42:43], 19
	s_add_u32 s54, s10, s42
	s_addc_u32 s55, s11, s43
	s_add_u32 s36, s54, 0x12f00000
	s_addc_u32 s18, s55, 0
	s_lshl_b32 s42, s20, 14
	s_ashr_i32 s43, s42, 31
	s_lshl_b64 s[42:43], s[42:43], 2
	s_add_u32 s20, s10, s42
	s_addc_u32 s42, s11, s43
	s_add_u32 s20, s20, 0x4000
	s_addc_u32 s92, s42, 0
	v_lshl_add_u64 v[2:3], v[2:3], 0, s[22:23]
	s_add_i32 m0, s21, 0x18000
	s_nop 1
	global_load_lds_dwordx4 v[2:3], off
	v_lshl_add_u64 v[2:3], v[4:5], 0, s[22:23]
	s_add_i32 m0, s21, 0x1a000
	s_add_i32 s56, s21, 0x8000
	s_add_i32 s57, s21, 0xa000
	global_load_lds_dwordx4 v[2:3], off
	v_lshl_add_u64 v[2:3], v[6:7], 0, s[22:23]
	s_mov_b32 m0, s56
	s_add_u32 s42, s50, 0x40080
	global_load_lds_dwordx4 v[2:3], off
	v_lshl_add_u64 v[2:3], v[8:9], 0, s[22:23]
	s_mov_b32 m0, s57
	s_addc_u32 s43, s51, 0
	global_load_lds_dwordx4 v[2:3], off
	v_lshl_add_u64 v[2:3], s[42:43], 0, v[0:1]
	s_add_i32 m0, s21, 0x1c000
	v_readlane_b32 s44, v253, 14
	global_load_lds_dwordx4 v[2:3], off
	v_lshl_add_u64 v[2:3], s[42:43], 0, v[134:135]
	s_add_i32 m0, s21, 0x1e000
	v_readlane_b32 s42, v253, 6
	global_load_lds_dwordx4 v[2:3], off
	s_waitcnt vmcnt(8)
	s_barrier
	v_and_b32_e32 v3, 15, v15
	v_bfe_u32 v2, v15, 4, 2
	v_or_b32_e32 v169, s42, v3
	v_lshlrev_b32_e32 v4, 6, v169
	v_lshlrev_b32_e32 v5, 4, v2
	s_movk_i32 s42, 0x3c0
	v_lshlrev_b32_e32 v6, 2, v169
	v_and_or_b32 v4, v4, s42, v5
	v_and_b32_e32 v7, 32, v6
	v_readlane_b32 s42, v253, 7
	v_lshl_or_b32 v5, v3, 6, v5
	s_add_i32 s60, 0, 0x21000
	v_bitop3_b32 v4, v4, s42, v7 bitop3:0xde
	v_lshlrev_b32_e32 v7, 2, v15
	v_and_b32_e32 v7, 32, v7
	v_readlane_b32 s42, v253, 9
	s_ashr_i32 s96, s29, 31
	s_waitcnt vmcnt(6)
	v_lshlrev_b32_e32 v3, 4, v3
	v_bitop3_b32 v170, v5, s42, v7 bitop3:0xde
	v_and_b32_e32 v5, 63, v15
	v_lshlrev_b32_e32 v7, 2, v5
	v_xor_b32_e32 v171, 64, v7
	v_or_b32_e32 v7, s44, v5
	s_movk_i32 s44, 0x100
	v_cmp_gt_i32_e64 s[44:45], s44, v7
	v_cmp_eq_u32_e64 s[46:47], 0, v5
	s_and_b64 s[64:65], s[46:47], s[44:45]
	v_lshl_add_u32 v179, v7, 4, s60
	s_add_i32 s60, 0, 0x22000
	s_cmp_lg_u64 s[48:49], 0
	v_readlane_b32 s48, v253, 8
	v_cmp_eq_u32_e64 s[42:43], 0, v2
	v_and_b32_e32 v5, 1, v10
	v_lshl_or_b32 v189, v2, 3, s48
	v_lshlrev_b32_e32 v2, 14, v10
	v_and_b32_e32 v2, 0xffff8000, v2
	v_lshl_add_u32 v2, v11, 11, v2
	v_lshl_or_b32 v2, v5, 6, v2
	v_lshl_add_u32 v138, v12, 1, v2
	v_lshlrev_b32_e32 v2, 14, v13
	v_and_b32_e32 v2, 0xffff8000, v2
	v_lshl_add_u32 v2, v14, 11, v2
	v_and_b32_e32 v5, 1, v13
	v_lshlrev_b32_e32 v136, 2, v7
	v_or_b32_e32 v172, 16, v169
	v_or_b32_e32 v173, 32, v169
	v_or_b32_e32 v174, 48, v169
	v_add_u32_e32 v175, 0x80, v169
	v_add_u32_e32 v176, 0x90, v169
	v_add_u32_e32 v177, 0xa0, v169
	v_add_u32_e32 v178, 0xb0, v169
	s_cselect_b64 s[70:71], -1, 0
	s_add_u32 s97, s54, 0x12f40000
	v_lshl_or_b32 v2, v5, 6, v2
	v_readlane_b32 s48, v253, 17
	s_mov_b32 s86, 0
	v_ashrrev_i32_e32 v137, 31, v136
	v_add_u32_e32 v180, s60, v136
	v_add_u32_e32 v181, s60, v6
	v_lshl_add_u32 v182, v172, 2, s60
	v_lshl_add_u32 v183, v173, 2, s60
	v_lshl_add_u32 v184, v174, 2, s60
	v_lshl_add_u32 v185, v175, 2, s60
	v_lshl_add_u32 v186, v176, 2, s60
	v_lshl_add_u32 v187, v177, 2, s60
	v_lshl_add_u32 v188, v178, 2, s60
	s_addc_u32 s72, s55, 0
	v_mov_b32_e32 v139, v1
	v_lshl_add_u32 v140, v16, 1, v2
	v_mov_b32_e32 v141, v1
	v_add_u32_e32 v190, 0, v4
	v_add_u32_e32 v191, s48, v3
	s_barrier
	s_branch .LBB0_190

; #define PG8_STAGE(bufoff, gbase, voff) do { _Pragma("unroll") for (int _i = 0; _i < 2; ++_i) \
;         __builtin_amdgcn_global_load_lds((const unsigned*)((const char*)(gbase) + (voff)[_i]), (LAS unsigned*)(lds + (bufoff) + ldsw + _i * 8192), 16, 0, 0); } while (0)
; #define PG8_WAIT_V(n) asm volatile("s_waitcnt vmcnt(" #n ")" ::: "memory")
; #define PG8_BAR __builtin_amdgcn_s_barrier()
; template <class Epi, class Sched, bool ALIGN_EPI = true>
; __device__ __forceinline__ void gemm_phase(LAS unsigned char* lds, const int wave_s, const int K, const Sched& S, const Epi& E) {
;     ...
;     PG8_STAGE(PG8_SB(0, 0), cB, voffB); PG8_STAGE(PG8_SB(0, 1), cB + hstep, voffB); PG8_STAGE(PG8_SA(0, 0), cA, voffA); PG8_STAGE(PG8_SA(0, 1), cA + hstep, voffA);
;     if (wr == 1) PG8_BAR;
;     PG8_WAIT_V(2); PG8_BAR;
;     PG8_STAGE(PG8_SB(1, 0), cB + kstep, voffB); PG8_STAGE(PG8_SA(1, 0), cA + kstep, voffA); PG8_STAGE(PG8_SB(1, 1), cB + hstep + kstep, voffB);
;     PG8_WAIT_V(6); PG8_BAR;
.LBB0_281:
	s_add_u32 s14, s10, 0x6d00000
	s_addc_u32 s15, s11, 0
	s_add_u32 s34, s10, 0x8d00000
	s_addc_u32 s35, s11, 0
	v_readlane_b32 s18, v254, 60
	s_add_u32 s48, s10, 0xcd00000
	v_readlane_b32 s19, v254, 61
	s_mulk_i32 s18, 0xc00
	s_addc_u32 s49, s11, 0
	s_ashr_i32 s19, s18, 31
	s_lshl_b64 s[18:19], s[18:19], 2
	s_add_u32 s65, s42, s18
	v_and_b32_e32 v17, 15, v16
	v_readlane_b32 s18, v253, 6
	v_bfe_u32 v18, v16, 4, 2
	v_lshlrev_b32_e32 v20, 4, v18
	v_or_b32_e32 v170, s18, v17
	v_lshlrev_b32_e32 v19, 6, v170
	s_movk_i32 s18, 0x3c0
	v_lshlrev_b32_e32 v21, 2, v170
	s_addc_u32 s68, s43, s19
	v_and_or_b32 v19, v19, s18, v20
	v_and_b32_e32 v21, 32, v21
	v_readlane_b32 s18, v253, 7
	v_lshlrev_b32_e32 v16, 2, v16
	v_lshl_add_u64 v[2:3], v[2:3], 0, s[22:23]
	s_add_i32 m0, s7, 0x18000
	v_bitop3_b32 v19, v19, s18, v21 bitop3:0xde
	v_lshl_or_b32 v21, v17, 6, v20
	v_and_b32_e32 v16, 32, v16
	v_readlane_b32 s18, v253, 9
	s_nop 1
	global_load_lds_dwordx4 v[2:3], off
	v_lshl_add_u64 v[2:3], v[4:5], 0, s[22:23]
	s_add_i32 m0, s7, 0x1a000
	s_add_i32 s69, s7, 0x8000
	s_add_i32 s70, s7, 0xa000
	v_bitop3_b32 v171, v21, s18, v16 bitop3:0xde
	global_load_lds_dwordx4 v[2:3], off
	v_lshl_add_u64 v[2:3], v[6:7], 0, s[22:23]
	s_mov_b32 m0, s69
	s_add_u32 s18, s44, 0x40080
	global_load_lds_dwordx4 v[2:3], off
	v_lshl_add_u64 v[2:3], v[8:9], 0, s[22:23]
	s_mov_b32 m0, s70
	s_addc_u32 s19, s45, 0
	global_load_lds_dwordx4 v[2:3], off
	v_lshl_add_u64 v[2:3], s[18:19], 0, v[0:1]
	s_add_i32 m0, s7, 0x1c000
	v_mov_b32_e32 v149, v1
	global_load_lds_dwordx4 v[2:3], off
	v_lshl_add_u64 v[2:3], s[18:19], 0, v[138:139]
	s_add_i32 m0, s7, 0x1e000
	v_readlane_b32 s18, v253, 22
	global_load_lds_dwordx4 v[2:3], off
	s_waitcnt vmcnt(8)
	s_barrier
	v_lshlrev_b32_e32 v2, 14, v13
	v_and_b32_e32 v2, 0xffff8000, v2
	v_lshl_add_u32 v2, v14, 11, v2
	v_and_b32_e32 v3, 1, v13
	v_lshl_or_b32 v2, v3, 6, v2
	v_lshl_add_u32 v148, v15, 1, v2
	v_lshlrev_b32_e32 v2, 14, v10
	v_and_b32_e32 v2, 0xffff8000, v2
	s_waitcnt vmcnt(6)
	v_or3_b32 v144, v20, s18, v17
	v_readlane_b32 s18, v253, 8
	v_lshl_add_u32 v2, v11, 11, v2
	v_and_b32_e32 v3, 1, v10
	v_ashrrev_i32_e32 v145, 31, v144
	v_lshl_or_b32 v172, v18, 3, s18
	v_lshl_or_b32 v2, v3, 6, v2
	v_readlane_b32 s18, v254, 25
	v_lshl_add_u64 v[146:147], v[144:145], 4, s[14:15]
	v_lshl_add_u32 v150, v12, 1, v2
	v_mov_b32_e32 v151, v1
	s_mov_b32 s21, 0
	v_add_u32_e32 v173, 0, v19
	v_readlane_b32 s28, v254, 22
	s_mov_b32 s20, s18
	s_mov_b32 s71, 0
	s_barrier
	v_readlane_b32 s19, v254, 26
	s_branch .LBB0_284

; #define PG8_STAGE(bufoff, gbase, voff) do { _Pragma("unroll") for (int _i = 0; _i < 2; ++_i) \
;         __builtin_amdgcn_global_load_lds((const unsigned*)((const char*)(gbase) + (voff)[_i]), (LAS unsigned*)(lds + (bufoff) + ldsw + _i * 8192), 16, 0, 0); } while (0)
; #define PG8_WAIT_V(n) asm volatile("s_waitcnt vmcnt(" #n ")" ::: "memory")
; #define PG8_BAR __builtin_amdgcn_s_barrier()
; template <class Epi, class Sched, bool ALIGN_EPI = true>
; __device__ __forceinline__ void gemm_phase(LAS unsigned char* lds, const int wave_s, const int K, const Sched& S, const Epi& E) {
;     ...
;     PG8_STAGE(PG8_SB(0, 0), cB, voffB); PG8_STAGE(PG8_SB(0, 1), cB + hstep, voffB); PG8_STAGE(PG8_SA(0, 0), cA, voffA); PG8_STAGE(PG8_SA(0, 1), cA + hstep, voffA);
;     if (wr == 1) PG8_BAR;
;     PG8_WAIT_V(2); PG8_BAR;
;     PG8_STAGE(PG8_SB(1, 0), cB + kstep, voffB); PG8_STAGE(PG8_SA(1, 0), cA + kstep, voffA); PG8_STAGE(PG8_SB(1, 1), cB + hstep + kstep, voffB);
;     PG8_WAIT_V(6); PG8_BAR;
.LBB0_416:
	s_add_u32 s50, s10, 0x6d00000
	s_addc_u32 s51, s11, 0
	s_add_u32 s54, s10, 0xed00000
	s_addc_u32 s55, s11, 0
	s_add_u32 s82, s10, 0x8d00000
	s_addc_u32 s83, s11, 0
	s_add_u32 s62, s10, 0x10d00000
	s_addc_u32 s63, s11, 0
	s_add_u32 s84, s10, 0xcd00000
	s_addc_u32 s85, s11, 0
	s_add_u32 s52, s10, 0xad00000
	s_addc_u32 s53, s11, 0
	s_add_u32 s94, s10, 0x12d00000
	s_addc_u32 s95, s11, 0
	v_lshl_add_u64 v[6:7], v[6:7], 0, s[22:23]
	s_add_i32 m0, s7, 0x18000
	s_nop 1
	global_load_lds_dwordx4 v[6:7], off
	v_lshl_add_u64 v[4:5], v[4:5], 0, s[22:23]
	s_add_i32 m0, s7, 0x1a000
	s_add_i32 s69, s7, 0x8000
	s_add_i32 s78, s7, 0xa000
	global_load_lds_dwordx4 v[4:5], off
	v_lshl_add_u64 v[2:3], v[2:3], 0, s[22:23]
	s_mov_b32 m0, s69
	s_add_u32 s14, s34, 0x40080
	global_load_lds_dwordx4 v[2:3], off
	v_lshl_add_u64 v[2:3], v[8:9], 0, s[22:23]
	s_mov_b32 m0, s78
	s_addc_u32 s15, s35, 0
	global_load_lds_dwordx4 v[2:3], off
	v_lshl_add_u64 v[2:3], s[14:15], 0, v[132:133]
	s_add_i32 m0, s7, 0x1c000
	s_mov_b32 s79, 0
	global_load_lds_dwordx4 v[2:3], off
	v_lshl_add_u64 v[2:3], s[14:15], 0, v[136:137]
	s_add_i32 m0, s7, 0x1e000
	v_readlane_b32 s14, v253, 6
	global_load_lds_dwordx4 v[2:3], off
	s_waitcnt vmcnt(8)
	s_barrier
	v_and_b32_e32 v2, 15, v13
	v_bfe_u32 v3, v13, 4, 2
	v_or_b32_e32 v174, s14, v2
	v_lshlrev_b32_e32 v4, 6, v174
	v_lshlrev_b32_e32 v6, 4, v3
	s_movk_i32 s14, 0x3c0
	v_lshlrev_b32_e32 v7, 2, v174
	v_and_or_b32 v4, v4, s14, v6
	v_and_b32_e32 v7, 32, v7
	v_readlane_b32 s14, v253, 7
	v_lshlrev_b32_e32 v5, 3, v3
	v_cmp_eq_u32_e64 s[42:43], 0, v3
	v_bitop3_b32 v7, v4, s14, v7 bitop3:0xde
	v_lshl_or_b32 v4, v2, 6, v6
	v_lshlrev_b32_e32 v2, 2, v2
	v_and_b32_e32 v6, 32, v2
	v_readlane_b32 s14, v253, 9
	s_waitcnt vmcnt(6)
	v_mov_b32_e32 v139, v1
	v_mov_b32_e32 v141, v1
	v_bitop3_b32 v175, v4, s14, v6 bitop3:0xde
	v_lshlrev_b32_e32 v4, 6, v3
	v_lshlrev_b32_e32 v3, 2, v3
	v_bitop3_b32 v176, v4, 64, v2 bitop3:0x36
	v_and_b32_e32 v4, 4, v3
	v_or_b32_e32 v6, 8, v3
	v_lshlrev_b32_e32 v3, 14, v0
	v_and_b32_e32 v3, 0xffff8000, v3
	v_lshl_add_u32 v3, v10, 11, v3
	v_and_b32_e32 v0, 1, v0
	v_lshl_or_b32 v0, v0, 6, v3
	v_lshl_add_u32 v138, v11, 1, v0
	v_lshlrev_b32_e32 v0, 14, v12
	v_and_b32_e32 v0, 0xffff8000, v0
	v_lshl_add_u32 v0, v14, 11, v0
	v_and_b32_e32 v3, 1, v12
	v_and_b32_e32 v2, 16, v5
	v_readlane_b32 s14, v253, 8
	v_lshl_or_b32 v0, v3, 6, v0
	v_lshl_add_u32 v140, v15, 1, v0
	v_or_b32_e32 v177, s14, v5
	v_add_u32_e32 v178, 0, v7
	v_lshlrev_b32_e32 v142, 1, v2
	v_lshlrev_b32_e32 v144, 1, v4
	v_lshlrev_b32_e32 v146, 1, v6
	s_barrier
	s_branch .LBB0_419
